# mixer-in/LoRA GEMM epilogue: the eight RMS row-scale chains (load, 2 bpermute, rsq) issued together instead of serially
# speedup vs baseline: 1.0062x; 1.0044x over previous
; __device__ __forceinline__ float row_rs(const float* ss, int r, int fq) { const f32x4 a = *(const f32x4*)(ss + (size_t)r * 16 + 4 * fq);
;     float t = (a[0] + a[1]) + (a[2] + a[3]); t += __shfl_xor(t, 16); t += __shfl_xor(t, 32); return __builtin_amdgcn_rsqf(t * (1.0f / 1024.0f) + 1e-6f); }
;     __device__ __forceinline__ void operator()(const f32x4 (&acc)[2][2][4][2], const Unit& u, int wr, int wc, int fr, int fq) const {
;     ...
;         float rsv[2][4];
; #pragma unroll
;         for (int ai = 0; ai < 2; ++ai)
; #pragma unroll
;             for (int m = 0; m < 4; ++m) rsv[ai][m] = ss ? row_rs(ss, row0 + ai * HALF + m * 16, fq) : 1.0f;
.LBB0_380:
	v_lshl_add_u32 v200, s55, 8, v187
	s_andn2_b64 vcc, exec, s[46:47]
	v_ashrrev_i32_e32 v201, 31, v200
	s_cbranch_vccnz .Lmx_noscale
	v_lshlrev_b64 v[148:149], 6, v[200:201]
	v_lshl_add_u64 v[148:149], v[188:189], 0, v[148:149]
	v_add_co_u32_e32 v154, vcc, 0x2000, v148
	v_xor_b32_e32 v170, 16, v236
	v_xor_b32_e32 v171, 32, v236
	v_addc_co_u32_e32 v155, vcc, 0, v149, vcc
	global_load_dwordx4 v[150:153], v[148:149], off
	global_load_dwordx4 v[158:161], v[148:149], off offset:1024
	global_load_dwordx4 v[162:165], v[148:149], off offset:2048
	global_load_dwordx4 v[166:169], v[148:149], off offset:3072
	global_load_dwordx4 v[202:205], v[154:155], off
	global_load_dwordx4 v[206:209], v[154:155], off offset:1024
	global_load_dwordx4 v[210:213], v[154:155], off offset:2048
	global_load_dwordx4 v[214:217], v[154:155], off offset:3072
	v_lshlrev_b32_e32 v170, 2, v170
	v_lshlrev_b32_e32 v171, 2, v171
	s_waitcnt vmcnt(7)
	v_add_f32_e32 v150, v151, v150
	v_add_f32_e32 v152, v152, v153
	v_add_f32_e32 v150, v150, v152
	ds_bpermute_b32 v151, v170, v150
	s_waitcnt vmcnt(6)
	v_add_f32_e32 v158, v159, v158
	v_add_f32_e32 v160, v160, v161
	v_add_f32_e32 v158, v158, v160
	ds_bpermute_b32 v159, v170, v158
	s_waitcnt vmcnt(5)
	v_add_f32_e32 v162, v163, v162
	v_add_f32_e32 v164, v164, v165
	v_add_f32_e32 v162, v162, v164
	ds_bpermute_b32 v163, v170, v162
	s_waitcnt vmcnt(4)
	v_add_f32_e32 v166, v167, v166
	v_add_f32_e32 v168, v168, v169
	v_add_f32_e32 v166, v166, v168
	ds_bpermute_b32 v167, v170, v166
	s_waitcnt vmcnt(3)
	v_add_f32_e32 v202, v203, v202
	v_add_f32_e32 v204, v204, v205
	v_add_f32_e32 v202, v202, v204
	ds_bpermute_b32 v203, v170, v202
	s_waitcnt vmcnt(2)
	v_add_f32_e32 v206, v207, v206
	v_add_f32_e32 v208, v208, v209
	v_add_f32_e32 v206, v206, v208
	ds_bpermute_b32 v207, v170, v206
	s_waitcnt vmcnt(1)
	v_add_f32_e32 v210, v211, v210
	v_add_f32_e32 v212, v212, v213
	v_add_f32_e32 v210, v210, v212
	ds_bpermute_b32 v211, v170, v210
	s_waitcnt vmcnt(0)
	v_add_f32_e32 v214, v215, v214
	v_add_f32_e32 v216, v216, v217
	v_add_f32_e32 v214, v214, v216
	ds_bpermute_b32 v215, v170, v214
	s_waitcnt lgkmcnt(7)
	v_add_f32_e32 v150, v150, v151
	ds_bpermute_b32 v151, v171, v150
	s_waitcnt lgkmcnt(7)
	v_add_f32_e32 v158, v158, v159
	ds_bpermute_b32 v159, v171, v158
	s_waitcnt lgkmcnt(7)
	v_add_f32_e32 v162, v162, v163
	ds_bpermute_b32 v163, v171, v162
	s_waitcnt lgkmcnt(7)
	v_add_f32_e32 v166, v166, v167
	ds_bpermute_b32 v167, v171, v166
	s_waitcnt lgkmcnt(7)
	v_add_f32_e32 v202, v202, v203
	ds_bpermute_b32 v203, v171, v202
	s_waitcnt lgkmcnt(7)
	v_add_f32_e32 v206, v206, v207
	ds_bpermute_b32 v207, v171, v206
	s_waitcnt lgkmcnt(7)
	v_add_f32_e32 v210, v210, v211
	ds_bpermute_b32 v211, v171, v210
	s_waitcnt lgkmcnt(7)
	v_add_f32_e32 v214, v214, v215
	ds_bpermute_b32 v215, v171, v214
	s_waitcnt lgkmcnt(7)
	v_add_f32_e32 v150, v150, v151
	v_fmamk_f32 v150, v150, 0x3a800000, v237
	s_waitcnt lgkmcnt(6)
	v_add_f32_e32 v158, v158, v159
	v_fmamk_f32 v158, v158, 0x3a800000, v237
	s_waitcnt lgkmcnt(5)
	v_add_f32_e32 v162, v162, v163
	v_fmamk_f32 v162, v162, 0x3a800000, v237
	s_waitcnt lgkmcnt(4)
	v_add_f32_e32 v166, v166, v167
	v_fmamk_f32 v166, v166, 0x3a800000, v237
	s_waitcnt lgkmcnt(3)
	v_add_f32_e32 v202, v202, v203
	v_fmamk_f32 v202, v202, 0x3a800000, v237
	s_waitcnt lgkmcnt(2)
	v_add_f32_e32 v206, v206, v207
	v_fmamk_f32 v206, v206, 0x3a800000, v237
	s_waitcnt lgkmcnt(1)
	v_add_f32_e32 v210, v210, v211
	v_fmamk_f32 v210, v210, 0x3a800000, v237
	s_waitcnt lgkmcnt(0)
	v_add_f32_e32 v214, v214, v215
	v_fmamk_f32 v214, v214, 0x3a800000, v237
	v_rsq_f32_e32 v194, v214
	v_rsq_f32_e32 v204, v210
	v_rsq_f32_e32 v206, v206
	v_rsq_f32_e32 v210, v202
	v_rsq_f32_e32 v214, v166
	v_rsq_f32_e32 v218, v162
	v_rsq_f32_e32 v222, v158
	v_rsq_f32_e32 v156, v150
	s_branch .Lmx_rows
.Lmx_noscale:
	v_mov_b32_e32 v156, 1.0
	v_mov_b32_e32 v222, 1.0
	v_mov_b32_e32 v218, 1.0
	v_mov_b32_e32 v214, 1.0
	v_mov_b32_e32 v210, 1.0
	v_mov_b32_e32 v206, 1.0
	v_mov_b32_e32 v204, 1.0
	v_mov_b32_e32 v194, 1.0
.Lmx_rows:
	v_or_b32_e32 v220, 16, v200
	v_or_b32_e32 v216, 32, v200
	v_or_b32_e32 v212, 48, v200
	v_add_u32_e32 v208, 0x80, v200
	v_ashrrev_i32_e32 v221, 31, v220
	v_ashrrev_i32_e32 v217, 31, v216
	v_ashrrev_i32_e32 v213, 31, v212
	v_ashrrev_i32_e32 v209, 31, v208
